# plus: LN row statistics exchanges via v_permlane16/32_swap (residual epilogue) and DPP lane permutes (spatial-gating LayerNorm) instead of ds_bpermute
# baseline (speedup 1.0000x reference)
.LBB0_778:
	s_lshr_b32 s0, s10, 2
	s_and_b32 s0, s0, 0x1fffff8
	s_and_b32 s1, s10, 7
	s_or_b32 s4, s0, s1
	s_mov_b64 s[0:1], s[86:87]
	v_mbcnt_lo_u32_b32 v51, -1, 0
	v_mbcnt_hi_u32_b32 v51, -1, v51
	s_add_u32 s2, s0, 0x9e84100
	v_add_u32_e32 v52, s75, v51
	s_addc_u32 s3, s1, 0
	s_lshl_b32 s12, s4, 7
	v_ashrrev_i32_e32 v53, 4, v52
	v_add_u32_e32 v18, s12, v53
	v_ashrrev_i32_e32 v19, 31, v18
	v_and_b32_e32 v50, 15, v51
	v_lshlrev_b64 v[2:3], 12, v[18:19]
	v_lshl_add_u64 v[2:3], s[2:3], 0, v[2:3]
	v_lshlrev_b32_e32 v0, 4, v50
	s_mov_b32 s7, 0x3727c5ac
	v_lshl_add_u64 v[14:15], v[2:3], 0, v[0:1]
	global_load_dwordx4 v[2:5], v[14:15], off offset:3072
	global_load_dwordx4 v[6:9], v[14:15], off offset:3328
	global_load_dwordx4 v[10:13], v[14:15], off offset:3584
	s_nop 0
	global_load_dwordx4 v[14:17], v[14:15], off offset:3840
	v_lshlrev_b32_e32 v19, 2, v51
	v_bitop3_b32 v57, v19, 4, v220 bitop3:0x6c
	v_add_u32_e32 v20, 32, v18
	v_add_u32_e32 v22, 64, v18
	v_add_u32_e32 v18, 0x60, v18
	v_bitop3_b32 v56, v19, 8, v220 bitop3:0x6c
	v_bitop3_b32 v55, v19, 16, v220 bitop3:0x6c
	v_bitop3_b32 v54, v19, 32, v220 bitop3:0x6c
	v_ashrrev_i32_e32 v21, 31, v20
	v_ashrrev_i32_e32 v23, 31, v22
	v_ashrrev_i32_e32 v19, 31, v18
	v_lshlrev_b64 v[20:21], 12, v[20:21]
	v_lshlrev_b64 v[22:23], 12, v[22:23]
	v_lshlrev_b64 v[18:19], 12, v[18:19]
	v_lshl_add_u64 v[20:21], s[2:3], 0, v[20:21]
	v_lshl_add_u64 v[22:23], s[2:3], 0, v[22:23]
	v_readlane_b32 s4, v254, 18
	v_cmp_eq_u32_e32 vcc, 0, v50
	s_waitcnt vmcnt(0)
	v_lshlrev_b32_e32 v59, 16, v2
	v_and_b32_e32 v60, 0xffff0000, v2
	v_lshlrev_b32_e32 v61, 16, v3
	v_and_b32_e32 v62, 0xffff0000, v3
	v_add_f32_e32 v2, v59, v60
	v_lshlrev_b32_e32 v63, 16, v4
	v_and_b32_e32 v64, 0xffff0000, v4
	v_add_f32_e32 v3, v61, v62
	v_add_f32_e32 v2, 0, v2
	v_lshlrev_b32_e32 v65, 16, v5
	v_and_b32_e32 v66, 0xffff0000, v5
	v_add_f32_e32 v4, v63, v64
	v_add_f32_e32 v2, v3, v2
	v_lshlrev_b32_e32 v67, 16, v6
	v_and_b32_e32 v68, 0xffff0000, v6
	v_add_f32_e32 v5, v65, v66
	v_add_f32_e32 v2, v4, v2
	v_lshlrev_b32_e32 v69, 16, v7
	v_and_b32_e32 v70, 0xffff0000, v7
	v_add_f32_e32 v6, v67, v68
	v_add_f32_e32 v2, v5, v2
	v_lshlrev_b32_e32 v71, 16, v8
	v_and_b32_e32 v72, 0xffff0000, v8
	v_add_f32_e32 v7, v69, v70
	v_add_f32_e32 v2, v6, v2
	v_lshlrev_b32_e32 v73, 16, v9
	v_and_b32_e32 v74, 0xffff0000, v9
	v_add_f32_e32 v8, v71, v72
	v_add_f32_e32 v2, v7, v2
	v_lshlrev_b32_e32 v75, 16, v10
	v_and_b32_e32 v76, 0xffff0000, v10
	v_add_f32_e32 v9, v73, v74
	v_add_f32_e32 v2, v8, v2
	v_lshlrev_b32_e32 v77, 16, v11
	v_and_b32_e32 v78, 0xffff0000, v11
	v_add_f32_e32 v10, v75, v76
	v_add_f32_e32 v2, v9, v2
	v_lshlrev_b32_e32 v79, 16, v12
	v_and_b32_e32 v80, 0xffff0000, v12
	v_add_f32_e32 v11, v77, v78
	v_add_f32_e32 v2, v10, v2
	v_lshlrev_b32_e32 v81, 16, v13
	v_and_b32_e32 v82, 0xffff0000, v13
	v_add_f32_e32 v12, v79, v80
	v_add_f32_e32 v2, v11, v2
	v_lshlrev_b32_e32 v83, 16, v14
	v_and_b32_e32 v84, 0xffff0000, v14
	v_add_f32_e32 v13, v81, v82
	v_add_f32_e32 v2, v12, v2
	v_lshlrev_b32_e32 v85, 16, v15
	v_and_b32_e32 v86, 0xffff0000, v15
	v_add_f32_e32 v14, v83, v84
	v_add_f32_e32 v2, v13, v2
	v_lshlrev_b32_e32 v87, 16, v16
	v_and_b32_e32 v88, 0xffff0000, v16
	v_add_f32_e32 v15, v85, v86
	v_add_f32_e32 v2, v14, v2
	v_lshlrev_b32_e32 v89, 16, v17
	v_and_b32_e32 v90, 0xffff0000, v17
	v_add_f32_e32 v16, v87, v88
	v_add_f32_e32 v2, v15, v2
	v_add_f32_e32 v17, v89, v90
	v_add_f32_e32 v2, v16, v2
	v_add_f32_e32 v8, v17, v2
	s_nop 1
	v_mov_b32_dpp v9, v8 quad_perm:[1,0,3,2] row_mask:0xf bank_mask:0xf
	v_lshl_add_u64 v[2:3], s[2:3], 0, v[18:19]
	v_lshl_add_u64 v[4:5], v[20:21], 0, v[0:1]
	v_lshl_add_u64 v[6:7], v[22:23], 0, v[0:1]
	v_lshl_add_u64 v[2:3], v[2:3], 0, v[0:1]
	s_waitcnt lgkmcnt(0)
	v_add_f32_e32 v0, v8, v9
	s_nop 1
	v_mov_b32_dpp v8, v0 quad_perm:[2,3,0,1] row_mask:0xf bank_mask:0xf
	global_load_dwordx4 v[46:49], v[4:5], off offset:3072
	global_load_dwordx4 v[42:45], v[4:5], off offset:3328
	global_load_dwordx4 v[38:41], v[4:5], off offset:3584
	global_load_dwordx4 v[34:37], v[4:5], off offset:3840
	global_load_dwordx4 v[30:33], v[6:7], off offset:3072
	global_load_dwordx4 v[26:29], v[6:7], off offset:3328
	global_load_dwordx4 v[22:25], v[6:7], off offset:3584
	global_load_dwordx4 v[18:21], v[6:7], off offset:3840
	s_waitcnt lgkmcnt(0)
	v_add_f32_e32 v0, v0, v8
	s_nop 1
	v_mov_b32_dpp v4, v0 row_half_mirror row_mask:0xf bank_mask:0xf
	s_waitcnt lgkmcnt(0)
	v_add_f32_e32 v0, v0, v4
	global_load_dwordx4 v[14:17], v[2:3], off offset:3072
	global_load_dwordx4 v[10:13], v[2:3], off offset:3328
	global_load_dwordx4 v[6:9], v[2:3], off offset:3584
	s_nop 0
	global_load_dwordx4 v[2:5], v[2:3], off offset:3840
	s_nop 1
	v_mov_b32_dpp v58, v0 row_mirror row_mask:0xf bank_mask:0xf
	s_waitcnt lgkmcnt(0)
	v_add_f32_e32 v58, v0, v58
	v_fmac_f32_e32 v60, 0xbb000000, v58
	v_fmac_f32_e32 v59, 0xbb000000, v58
	v_fmac_f32_e32 v62, 0xbb000000, v58
	v_mul_f32_e32 v0, v60, v60
	v_fmac_f32_e32 v61, 0xbb000000, v58
	v_fmac_f32_e32 v0, v59, v59
	v_mul_f32_e32 v59, v62, v62
	v_fmac_f32_e32 v59, v61, v61
	v_fmac_f32_e32 v64, 0xbb000000, v58
	v_add_f32_e32 v0, v0, v59
	v_fmac_f32_e32 v63, 0xbb000000, v58
	v_mul_f32_e32 v59, v64, v64
	v_fmac_f32_e32 v59, v63, v63
	v_fmac_f32_e32 v66, 0xbb000000, v58
	v_add_f32_e32 v0, v59, v0
	v_fmac_f32_e32 v65, 0xbb000000, v58
	v_mul_f32_e32 v59, v66, v66
	v_fmac_f32_e32 v59, v65, v65
	v_fmac_f32_e32 v68, 0xbb000000, v58
	v_add_f32_e32 v0, v59, v0
	v_fmac_f32_e32 v67, 0xbb000000, v58
	v_mul_f32_e32 v59, v68, v68
	v_fmac_f32_e32 v59, v67, v67
	v_fmac_f32_e32 v70, 0xbb000000, v58
	v_add_f32_e32 v0, v59, v0
	v_fmac_f32_e32 v69, 0xbb000000, v58
	v_mul_f32_e32 v59, v70, v70
	v_fmac_f32_e32 v59, v69, v69
	v_fmac_f32_e32 v72, 0xbb000000, v58
	v_add_f32_e32 v0, v59, v0
	v_fmac_f32_e32 v71, 0xbb000000, v58
	v_mul_f32_e32 v59, v72, v72
	v_fmac_f32_e32 v59, v71, v71
	v_fmac_f32_e32 v74, 0xbb000000, v58
	v_add_f32_e32 v0, v59, v0
	v_fmac_f32_e32 v73, 0xbb000000, v58
	v_mul_f32_e32 v59, v74, v74
	v_fmac_f32_e32 v59, v73, v73
	v_fmac_f32_e32 v76, 0xbb000000, v58
	v_add_f32_e32 v0, v59, v0
	v_fmac_f32_e32 v75, 0xbb000000, v58
	v_mul_f32_e32 v59, v76, v76
	v_fmac_f32_e32 v59, v75, v75
	v_fmac_f32_e32 v78, 0xbb000000, v58
	v_add_f32_e32 v0, v59, v0
	v_fmac_f32_e32 v77, 0xbb000000, v58
	v_mul_f32_e32 v59, v78, v78
	v_fmac_f32_e32 v59, v77, v77
	v_fmac_f32_e32 v80, 0xbb000000, v58
	v_add_f32_e32 v0, v59, v0
	v_fmac_f32_e32 v79, 0xbb000000, v58
	v_mul_f32_e32 v59, v80, v80
	v_fmac_f32_e32 v59, v79, v79
	v_fmac_f32_e32 v82, 0xbb000000, v58
	v_add_f32_e32 v0, v59, v0
	v_fmac_f32_e32 v81, 0xbb000000, v58
	v_mul_f32_e32 v59, v82, v82
	v_fmac_f32_e32 v59, v81, v81
	v_fmac_f32_e32 v84, 0xbb000000, v58
	v_add_f32_e32 v0, v59, v0
	v_fmac_f32_e32 v83, 0xbb000000, v58
	v_mul_f32_e32 v59, v84, v84
	v_fmac_f32_e32 v59, v83, v83
	v_fmac_f32_e32 v86, 0xbb000000, v58
	v_add_f32_e32 v0, v59, v0
	v_fmac_f32_e32 v85, 0xbb000000, v58
	v_mul_f32_e32 v59, v86, v86
	v_fmac_f32_e32 v59, v85, v85
	v_fmac_f32_e32 v88, 0xbb000000, v58
	v_add_f32_e32 v0, v59, v0
	v_fmac_f32_e32 v87, 0xbb000000, v58
	v_mul_f32_e32 v59, v88, v88
	v_fmac_f32_e32 v59, v87, v87
	v_fmac_f32_e32 v90, 0xbb000000, v58
	v_add_f32_e32 v0, v59, v0
	v_fmac_f32_e32 v89, 0xbb000000, v58
	v_mul_f32_e32 v59, v90, v90
	v_fmac_f32_e32 v59, v89, v89
	v_add_f32_e32 v0, v59, v0
	s_nop 1
	v_mov_b32_dpp v59, v0 quad_perm:[1,0,3,2] row_mask:0xf bank_mask:0xf
	s_waitcnt lgkmcnt(0)
	v_add_f32_e32 v0, v0, v59
	s_nop 1
	v_mov_b32_dpp v59, v0 quad_perm:[2,3,0,1] row_mask:0xf bank_mask:0xf
	s_waitcnt lgkmcnt(0)
	v_add_f32_e32 v0, v0, v59
	s_nop 1
	v_mov_b32_dpp v59, v0 row_half_mirror row_mask:0xf bank_mask:0xf
	s_waitcnt lgkmcnt(0)
	v_add_f32_e32 v59, v0, v59
	s_nop 1
	v_mov_b32_dpp v60, v59 row_mirror row_mask:0xf bank_mask:0xf
	v_lshl_add_u32 v0, v53, 3, s4
	s_and_saveexec_b64 s[4:5], vcc
	s_cbranch_execz .LBB0_780
	s_waitcnt lgkmcnt(0)
	v_add_f32_e32 v59, v59, v60
	v_mov_b32_e32 v60, s7
	v_fmamk_f32 v59, v59, 0x3b000000, v60
	v_rsq_f32_e32 v59, v59
	v_mul_f32_e32 v58, 0x3b000000, v58
	ds_write_b64 v0, v[58:59]
.LBB0_780:
	s_or_b64 exec, exec, s[4:5]
	s_waitcnt vmcnt(11)
	v_lshlrev_b32_e32 v58, 16, v46
	v_and_b32_e32 v46, 0xffff0000, v46
	v_add_f32_e32 v59, v58, v46
	s_waitcnt lgkmcnt(0)
	v_lshlrev_b32_e32 v60, 16, v47
	v_and_b32_e32 v47, 0xffff0000, v47
	v_add_f32_e32 v59, 0, v59
	v_add_f32_e32 v61, v60, v47
	v_add_f32_e32 v59, v61, v59
	v_lshlrev_b32_e32 v61, 16, v48
	v_and_b32_e32 v48, 0xffff0000, v48
	v_add_f32_e32 v62, v61, v48
	v_add_f32_e32 v59, v62, v59
	v_lshlrev_b32_e32 v62, 16, v49
	v_and_b32_e32 v49, 0xffff0000, v49
	v_add_f32_e32 v63, v62, v49
	v_add_f32_e32 v59, v63, v59
	s_waitcnt vmcnt(10)
	v_lshlrev_b32_e32 v63, 16, v42
	v_and_b32_e32 v42, 0xffff0000, v42
	v_add_f32_e32 v64, v63, v42
	v_add_f32_e32 v59, v64, v59
	v_lshlrev_b32_e32 v64, 16, v43
	v_and_b32_e32 v43, 0xffff0000, v43
	v_add_f32_e32 v65, v64, v43
	v_add_f32_e32 v59, v65, v59
	v_lshlrev_b32_e32 v65, 16, v44
	v_and_b32_e32 v44, 0xffff0000, v44
	v_add_f32_e32 v66, v65, v44
	v_add_f32_e32 v59, v66, v59
	v_lshlrev_b32_e32 v66, 16, v45
	v_and_b32_e32 v45, 0xffff0000, v45
	v_add_f32_e32 v67, v66, v45
	v_add_f32_e32 v59, v67, v59
	s_waitcnt vmcnt(9)
	v_lshlrev_b32_e32 v67, 16, v38
	v_and_b32_e32 v38, 0xffff0000, v38
	v_add_f32_e32 v68, v67, v38
	v_add_f32_e32 v59, v68, v59
	v_lshlrev_b32_e32 v68, 16, v39
	v_and_b32_e32 v39, 0xffff0000, v39
	v_add_f32_e32 v69, v68, v39
	v_add_f32_e32 v59, v69, v59
	v_lshlrev_b32_e32 v69, 16, v40
	v_and_b32_e32 v40, 0xffff0000, v40
	v_add_f32_e32 v70, v69, v40
	v_add_f32_e32 v59, v70, v59
	v_lshlrev_b32_e32 v70, 16, v41
	v_and_b32_e32 v41, 0xffff0000, v41
	v_add_f32_e32 v71, v70, v41
	v_add_f32_e32 v59, v71, v59
	s_waitcnt vmcnt(8)
	v_lshlrev_b32_e32 v71, 16, v34
	v_and_b32_e32 v72, 0xffff0000, v34
	v_add_f32_e32 v34, v71, v72
	v_add_f32_e32 v34, v34, v59
	v_lshlrev_b32_e32 v59, 16, v35
	v_and_b32_e32 v35, 0xffff0000, v35
	v_add_f32_e32 v73, v59, v35
	v_add_f32_e32 v34, v73, v34
	v_lshlrev_b32_e32 v73, 16, v36
	v_and_b32_e32 v36, 0xffff0000, v36
	v_add_f32_e32 v74, v73, v36
	v_add_f32_e32 v34, v74, v34
	v_lshlrev_b32_e32 v74, 16, v37
	v_and_b32_e32 v37, 0xffff0000, v37
	v_add_f32_e32 v75, v74, v37
	v_add_f32_e32 v34, v75, v34
	s_nop 1
	v_mov_b32_dpp v75, v34 quad_perm:[1,0,3,2] row_mask:0xf bank_mask:0xf
	s_waitcnt lgkmcnt(0)
	v_add_f32_e32 v34, v34, v75
	s_nop 1
	v_mov_b32_dpp v75, v34 quad_perm:[2,3,0,1] row_mask:0xf bank_mask:0xf
	s_waitcnt lgkmcnt(0)
	v_add_f32_e32 v34, v34, v75
	s_nop 1
	v_mov_b32_dpp v75, v34 row_half_mirror row_mask:0xf bank_mask:0xf
	s_waitcnt lgkmcnt(0)
	v_add_f32_e32 v34, v34, v75
	s_nop 1
	v_mov_b32_dpp v75, v34 row_mirror row_mask:0xf bank_mask:0xf
	s_waitcnt lgkmcnt(0)
	v_add_f32_e32 v34, v34, v75
	v_fmac_f32_e32 v46, 0xbb000000, v34
	v_fmac_f32_e32 v47, 0xbb000000, v34
	v_fmac_f32_e32 v58, 0xbb000000, v34
	v_mul_f32_e32 v46, v46, v46
	v_fmac_f32_e32 v60, 0xbb000000, v34
	v_mul_f32_e32 v47, v47, v47
	v_fmac_f32_e32 v46, v58, v58
	v_fmac_f32_e32 v47, v60, v60
	v_fmac_f32_e32 v48, 0xbb000000, v34
	v_add_f32_e32 v46, v46, v47
	v_fmac_f32_e32 v61, 0xbb000000, v34
	v_mul_f32_e32 v47, v48, v48
	v_fmac_f32_e32 v47, v61, v61
	v_fmac_f32_e32 v49, 0xbb000000, v34
	v_add_f32_e32 v46, v47, v46
	v_fmac_f32_e32 v62, 0xbb000000, v34
	v_mul_f32_e32 v47, v49, v49
	v_fmac_f32_e32 v42, 0xbb000000, v34
	v_fmac_f32_e32 v47, v62, v62
	v_fmac_f32_e32 v63, 0xbb000000, v34
	v_mul_f32_e32 v42, v42, v42
	v_fmac_f32_e32 v43, 0xbb000000, v34
	v_add_f32_e32 v46, v47, v46
	v_fmac_f32_e32 v42, v63, v63
	v_fmac_f32_e32 v64, 0xbb000000, v34
	v_mul_f32_e32 v43, v43, v43
	v_add_f32_e32 v42, v42, v46
	v_fmac_f32_e32 v43, v64, v64
	v_fmac_f32_e32 v44, 0xbb000000, v34
	v_add_f32_e32 v42, v43, v42
	v_fmac_f32_e32 v65, 0xbb000000, v34
	v_mul_f32_e32 v43, v44, v44
	v_fmac_f32_e32 v43, v65, v65
	v_fmac_f32_e32 v45, 0xbb000000, v34
	v_add_f32_e32 v42, v43, v42
	v_fmac_f32_e32 v66, 0xbb000000, v34
	v_mul_f32_e32 v43, v45, v45
	v_fmac_f32_e32 v38, 0xbb000000, v34
	v_fmac_f32_e32 v43, v66, v66
	v_fmac_f32_e32 v67, 0xbb000000, v34
	v_mul_f32_e32 v38, v38, v38
	v_fmac_f32_e32 v39, 0xbb000000, v34
	v_add_f32_e32 v42, v43, v42
	v_fmac_f32_e32 v38, v67, v67
	v_fmac_f32_e32 v68, 0xbb000000, v34
	v_mul_f32_e32 v39, v39, v39
	v_add_f32_e32 v38, v38, v42
	v_fmac_f32_e32 v39, v68, v68
	v_fmac_f32_e32 v40, 0xbb000000, v34
	v_add_f32_e32 v38, v39, v38
	v_fmac_f32_e32 v69, 0xbb000000, v34
	v_mul_f32_e32 v39, v40, v40
	v_fmac_f32_e32 v39, v69, v69
	v_fmac_f32_e32 v41, 0xbb000000, v34
	v_add_f32_e32 v38, v39, v38
	v_fmac_f32_e32 v70, 0xbb000000, v34
	v_mul_f32_e32 v39, v41, v41
	v_fmac_f32_e32 v39, v70, v70
	v_fmac_f32_e32 v72, 0xbb000000, v34
	v_add_f32_e32 v38, v39, v38
	v_fmac_f32_e32 v71, 0xbb000000, v34
	v_mul_f32_e32 v39, v72, v72
	v_fmac_f32_e32 v35, 0xbb000000, v34
	v_fmac_f32_e32 v39, v71, v71
	v_fmac_f32_e32 v59, 0xbb000000, v34
	v_mul_f32_e32 v35, v35, v35
	v_fmac_f32_e32 v36, 0xbb000000, v34
	v_add_f32_e32 v38, v39, v38
	v_fmac_f32_e32 v35, v59, v59
	v_fmac_f32_e32 v73, 0xbb000000, v34
	v_mul_f32_e32 v36, v36, v36
	v_add_f32_e32 v35, v35, v38
	v_fmac_f32_e32 v36, v73, v73
	v_fmac_f32_e32 v37, 0xbb000000, v34
	v_add_f32_e32 v35, v36, v35
	v_fmac_f32_e32 v74, 0xbb000000, v34
	v_mul_f32_e32 v36, v37, v37
	v_fmac_f32_e32 v36, v74, v74
	v_add_f32_e32 v35, v36, v35
	s_nop 1
	v_mov_b32_dpp v36, v35 quad_perm:[1,0,3,2] row_mask:0xf bank_mask:0xf
	s_waitcnt lgkmcnt(0)
	v_add_f32_e32 v35, v35, v36
	s_nop 1
	v_mov_b32_dpp v36, v35 quad_perm:[2,3,0,1] row_mask:0xf bank_mask:0xf
	s_waitcnt lgkmcnt(0)
	v_add_f32_e32 v35, v35, v36
	s_nop 1
	v_mov_b32_dpp v36, v35 row_half_mirror row_mask:0xf bank_mask:0xf
	s_waitcnt lgkmcnt(0)
	v_add_f32_e32 v35, v35, v36
	s_nop 1
	v_mov_b32_dpp v36, v35 row_mirror row_mask:0xf bank_mask:0xf
	s_and_saveexec_b64 s[4:5], vcc
	s_cbranch_execz .LBB0_782
	s_waitcnt lgkmcnt(0)
	v_add_f32_e32 v35, v35, v36
	v_mov_b32_e32 v36, s7
	v_fmamk_f32 v35, v35, 0x3b000000, v36
	v_rsq_f32_e32 v35, v35
	v_mul_f32_e32 v34, 0x3b000000, v34
	ds_write_b64 v0, v[34:35] offset:256
.LBB0_782:
	s_or_b64 exec, exec, s[4:5]
	s_waitcnt vmcnt(7)
	v_lshlrev_b32_e32 v34, 16, v30
	v_and_b32_e32 v30, 0xffff0000, v30
	v_add_f32_e32 v35, v34, v30
	s_waitcnt lgkmcnt(0)
	v_lshlrev_b32_e32 v36, 16, v31
	v_and_b32_e32 v31, 0xffff0000, v31
	v_add_f32_e32 v35, 0, v35
	v_add_f32_e32 v37, v36, v31
	v_add_f32_e32 v35, v37, v35
	v_lshlrev_b32_e32 v37, 16, v32
	v_and_b32_e32 v32, 0xffff0000, v32
	v_add_f32_e32 v38, v37, v32
	v_add_f32_e32 v35, v38, v35
	v_lshlrev_b32_e32 v38, 16, v33
	v_and_b32_e32 v33, 0xffff0000, v33
	v_add_f32_e32 v39, v38, v33
	v_add_f32_e32 v35, v39, v35
	s_waitcnt vmcnt(6)
	v_lshlrev_b32_e32 v39, 16, v26
	v_and_b32_e32 v26, 0xffff0000, v26
	v_add_f32_e32 v40, v39, v26
	v_add_f32_e32 v35, v40, v35
	v_lshlrev_b32_e32 v40, 16, v27
	v_and_b32_e32 v27, 0xffff0000, v27
	v_add_f32_e32 v41, v40, v27
	v_add_f32_e32 v35, v41, v35
	v_lshlrev_b32_e32 v41, 16, v28
	v_and_b32_e32 v28, 0xffff0000, v28
	v_add_f32_e32 v42, v41, v28
	v_add_f32_e32 v35, v42, v35
	v_lshlrev_b32_e32 v42, 16, v29
	v_and_b32_e32 v29, 0xffff0000, v29
	v_add_f32_e32 v43, v42, v29
	v_add_f32_e32 v35, v43, v35
	s_waitcnt vmcnt(5)
	v_lshlrev_b32_e32 v43, 16, v22
	v_and_b32_e32 v22, 0xffff0000, v22
	v_add_f32_e32 v44, v43, v22
	v_add_f32_e32 v35, v44, v35
	v_lshlrev_b32_e32 v44, 16, v23
	v_and_b32_e32 v23, 0xffff0000, v23
	v_add_f32_e32 v45, v44, v23
	v_add_f32_e32 v35, v45, v35
	v_lshlrev_b32_e32 v45, 16, v24
	v_and_b32_e32 v24, 0xffff0000, v24
	v_add_f32_e32 v46, v45, v24
	v_add_f32_e32 v35, v46, v35
	v_lshlrev_b32_e32 v46, 16, v25
	v_and_b32_e32 v25, 0xffff0000, v25
	v_add_f32_e32 v47, v46, v25
	v_add_f32_e32 v35, v47, v35
	s_waitcnt vmcnt(4)
	v_lshlrev_b32_e32 v47, 16, v18
	v_and_b32_e32 v48, 0xffff0000, v18
	v_add_f32_e32 v18, v47, v48
	v_add_f32_e32 v18, v18, v35
	v_lshlrev_b32_e32 v35, 16, v19
	v_and_b32_e32 v19, 0xffff0000, v19
	v_add_f32_e32 v49, v35, v19
	v_add_f32_e32 v18, v49, v18
	v_lshlrev_b32_e32 v49, 16, v20
	v_and_b32_e32 v20, 0xffff0000, v20
	v_add_f32_e32 v58, v49, v20
	v_add_f32_e32 v18, v58, v18
	v_lshlrev_b32_e32 v58, 16, v21
	v_and_b32_e32 v21, 0xffff0000, v21
	v_add_f32_e32 v59, v58, v21
	v_add_f32_e32 v18, v59, v18
	s_nop 1
	v_mov_b32_dpp v59, v18 quad_perm:[1,0,3,2] row_mask:0xf bank_mask:0xf
	s_waitcnt lgkmcnt(0)
	v_add_f32_e32 v18, v18, v59
	s_nop 1
	v_mov_b32_dpp v59, v18 quad_perm:[2,3,0,1] row_mask:0xf bank_mask:0xf
	s_waitcnt lgkmcnt(0)
	v_add_f32_e32 v18, v18, v59
	s_nop 1
	v_mov_b32_dpp v59, v18 row_half_mirror row_mask:0xf bank_mask:0xf
	s_waitcnt lgkmcnt(0)
	v_add_f32_e32 v18, v18, v59
	s_nop 1
	v_mov_b32_dpp v59, v18 row_mirror row_mask:0xf bank_mask:0xf
	s_waitcnt lgkmcnt(0)
	v_add_f32_e32 v18, v18, v59
	v_fmac_f32_e32 v30, 0xbb000000, v18
	v_fmac_f32_e32 v31, 0xbb000000, v18
	v_fmac_f32_e32 v34, 0xbb000000, v18
	v_mul_f32_e32 v30, v30, v30
	v_fmac_f32_e32 v36, 0xbb000000, v18
	v_mul_f32_e32 v31, v31, v31
	v_fmac_f32_e32 v30, v34, v34
	v_fmac_f32_e32 v31, v36, v36
	v_fmac_f32_e32 v32, 0xbb000000, v18
	v_add_f32_e32 v30, v30, v31
	v_fmac_f32_e32 v37, 0xbb000000, v18
	v_mul_f32_e32 v31, v32, v32
	v_fmac_f32_e32 v31, v37, v37
	v_fmac_f32_e32 v33, 0xbb000000, v18
	v_add_f32_e32 v30, v31, v30
	v_fmac_f32_e32 v38, 0xbb000000, v18
	v_mul_f32_e32 v31, v33, v33
	v_fmac_f32_e32 v26, 0xbb000000, v18
	v_fmac_f32_e32 v31, v38, v38
	v_fmac_f32_e32 v39, 0xbb000000, v18
	v_mul_f32_e32 v26, v26, v26
	v_fmac_f32_e32 v27, 0xbb000000, v18
	v_add_f32_e32 v30, v31, v30
	v_fmac_f32_e32 v26, v39, v39
	v_fmac_f32_e32 v40, 0xbb000000, v18
	v_mul_f32_e32 v27, v27, v27
	v_add_f32_e32 v26, v26, v30
	v_fmac_f32_e32 v27, v40, v40
	v_fmac_f32_e32 v28, 0xbb000000, v18
	v_add_f32_e32 v26, v27, v26
	v_fmac_f32_e32 v41, 0xbb000000, v18
	v_mul_f32_e32 v27, v28, v28
	v_fmac_f32_e32 v27, v41, v41
	v_fmac_f32_e32 v29, 0xbb000000, v18
	v_add_f32_e32 v26, v27, v26
	v_fmac_f32_e32 v42, 0xbb000000, v18
	v_mul_f32_e32 v27, v29, v29
	v_fmac_f32_e32 v22, 0xbb000000, v18
	v_fmac_f32_e32 v27, v42, v42
	v_fmac_f32_e32 v43, 0xbb000000, v18
	v_mul_f32_e32 v22, v22, v22
	v_fmac_f32_e32 v23, 0xbb000000, v18
	v_add_f32_e32 v26, v27, v26
	v_fmac_f32_e32 v22, v43, v43
	v_fmac_f32_e32 v44, 0xbb000000, v18
	v_mul_f32_e32 v23, v23, v23
	v_add_f32_e32 v22, v22, v26
	v_fmac_f32_e32 v23, v44, v44
	v_fmac_f32_e32 v24, 0xbb000000, v18
	v_add_f32_e32 v22, v23, v22
	v_fmac_f32_e32 v45, 0xbb000000, v18
	v_mul_f32_e32 v23, v24, v24
	v_fmac_f32_e32 v23, v45, v45
	v_fmac_f32_e32 v25, 0xbb000000, v18
	v_add_f32_e32 v22, v23, v22
	v_fmac_f32_e32 v46, 0xbb000000, v18
	v_mul_f32_e32 v23, v25, v25
	v_fmac_f32_e32 v23, v46, v46
	v_fmac_f32_e32 v48, 0xbb000000, v18
	v_add_f32_e32 v22, v23, v22
	v_fmac_f32_e32 v47, 0xbb000000, v18
	v_mul_f32_e32 v23, v48, v48
	v_fmac_f32_e32 v19, 0xbb000000, v18
	v_fmac_f32_e32 v23, v47, v47
	v_fmac_f32_e32 v35, 0xbb000000, v18
	v_mul_f32_e32 v19, v19, v19
	v_fmac_f32_e32 v20, 0xbb000000, v18
	v_add_f32_e32 v22, v23, v22
	v_fmac_f32_e32 v19, v35, v35
	v_fmac_f32_e32 v49, 0xbb000000, v18
	v_mul_f32_e32 v20, v20, v20
	v_add_f32_e32 v19, v19, v22
	v_fmac_f32_e32 v20, v49, v49
	v_fmac_f32_e32 v21, 0xbb000000, v18
	v_add_f32_e32 v19, v20, v19
	v_fmac_f32_e32 v58, 0xbb000000, v18
	v_mul_f32_e32 v20, v21, v21
	v_fmac_f32_e32 v20, v58, v58
	v_add_f32_e32 v19, v20, v19
	s_nop 1
	v_mov_b32_dpp v20, v19 quad_perm:[1,0,3,2] row_mask:0xf bank_mask:0xf
	s_waitcnt lgkmcnt(0)
	v_add_f32_e32 v19, v19, v20
	s_nop 1
	v_mov_b32_dpp v20, v19 quad_perm:[2,3,0,1] row_mask:0xf bank_mask:0xf
	s_waitcnt lgkmcnt(0)
	v_add_f32_e32 v19, v19, v20
	s_nop 1
	v_mov_b32_dpp v20, v19 row_half_mirror row_mask:0xf bank_mask:0xf
	s_waitcnt lgkmcnt(0)
	v_add_f32_e32 v19, v19, v20
	s_nop 1
	v_mov_b32_dpp v20, v19 row_mirror row_mask:0xf bank_mask:0xf
	s_and_saveexec_b64 s[4:5], vcc
	s_cbranch_execz .LBB0_784
	s_waitcnt lgkmcnt(0)
	v_add_f32_e32 v19, v19, v20
	v_mov_b32_e32 v20, s7
	v_fmamk_f32 v19, v19, 0x3b000000, v20
	v_rsq_f32_e32 v19, v19
	v_mul_f32_e32 v18, 0x3b000000, v18
	ds_write_b64 v0, v[18:19] offset:512
.LBB0_784:
	s_or_b64 exec, exec, s[4:5]
	s_waitcnt vmcnt(3)
	v_lshlrev_b32_e32 v18, 16, v14
	v_and_b32_e32 v14, 0xffff0000, v14
	v_add_f32_e32 v19, v18, v14
	s_waitcnt lgkmcnt(0)
	v_lshlrev_b32_e32 v20, 16, v15
	v_and_b32_e32 v15, 0xffff0000, v15
	v_add_f32_e32 v19, 0, v19
	v_add_f32_e32 v21, v20, v15
	v_add_f32_e32 v19, v21, v19
	v_lshlrev_b32_e32 v21, 16, v16
	v_and_b32_e32 v16, 0xffff0000, v16
	v_add_f32_e32 v22, v21, v16
	v_add_f32_e32 v19, v22, v19
	v_lshlrev_b32_e32 v22, 16, v17
	v_and_b32_e32 v17, 0xffff0000, v17
	v_add_f32_e32 v23, v22, v17
	v_add_f32_e32 v19, v23, v19
	s_waitcnt vmcnt(2)
	v_lshlrev_b32_e32 v23, 16, v10
	v_and_b32_e32 v10, 0xffff0000, v10
	v_add_f32_e32 v24, v23, v10
	v_add_f32_e32 v19, v24, v19
	v_lshlrev_b32_e32 v24, 16, v11
	v_and_b32_e32 v11, 0xffff0000, v11
	v_add_f32_e32 v25, v24, v11
	v_add_f32_e32 v19, v25, v19
	v_lshlrev_b32_e32 v25, 16, v12
	v_and_b32_e32 v12, 0xffff0000, v12
	v_add_f32_e32 v26, v25, v12
	v_add_f32_e32 v19, v26, v19
	v_lshlrev_b32_e32 v26, 16, v13
	v_and_b32_e32 v13, 0xffff0000, v13
	v_add_f32_e32 v27, v26, v13
	v_add_f32_e32 v19, v27, v19
	s_waitcnt vmcnt(1)
	v_lshlrev_b32_e32 v27, 16, v6
	v_and_b32_e32 v6, 0xffff0000, v6
	v_add_f32_e32 v28, v27, v6
	v_add_f32_e32 v19, v28, v19
	v_lshlrev_b32_e32 v28, 16, v7
	v_and_b32_e32 v7, 0xffff0000, v7
	v_add_f32_e32 v29, v28, v7
	v_add_f32_e32 v19, v29, v19
	v_lshlrev_b32_e32 v29, 16, v8
	v_and_b32_e32 v8, 0xffff0000, v8
	v_add_f32_e32 v30, v29, v8
	v_add_f32_e32 v19, v30, v19
	v_lshlrev_b32_e32 v30, 16, v9
	v_and_b32_e32 v9, 0xffff0000, v9
	v_add_f32_e32 v31, v30, v9
	v_add_f32_e32 v19, v31, v19
	s_waitcnt vmcnt(0)
	v_lshlrev_b32_e32 v31, 16, v2
	v_and_b32_e32 v32, 0xffff0000, v2
	v_add_f32_e32 v2, v31, v32
	v_add_f32_e32 v2, v2, v19
	v_lshlrev_b32_e32 v19, 16, v3
	v_and_b32_e32 v3, 0xffff0000, v3
	v_add_f32_e32 v33, v19, v3
	v_add_f32_e32 v2, v33, v2
	v_lshlrev_b32_e32 v33, 16, v4
	v_and_b32_e32 v4, 0xffff0000, v4
	v_add_f32_e32 v34, v33, v4
	v_add_f32_e32 v2, v34, v2
	v_lshlrev_b32_e32 v34, 16, v5
	v_and_b32_e32 v5, 0xffff0000, v5
	v_add_f32_e32 v35, v34, v5
	v_add_f32_e32 v2, v35, v2
	s_nop 1
	v_mov_b32_dpp v35, v2 quad_perm:[1,0,3,2] row_mask:0xf bank_mask:0xf
	s_waitcnt lgkmcnt(0)
	v_add_f32_e32 v2, v2, v35
	s_nop 1
	v_mov_b32_dpp v35, v2 quad_perm:[2,3,0,1] row_mask:0xf bank_mask:0xf
	s_waitcnt lgkmcnt(0)
	v_add_f32_e32 v2, v2, v35
	s_nop 1
	v_mov_b32_dpp v35, v2 row_half_mirror row_mask:0xf bank_mask:0xf
	s_waitcnt lgkmcnt(0)
	v_add_f32_e32 v2, v2, v35
	s_nop 1
	v_mov_b32_dpp v35, v2 row_mirror row_mask:0xf bank_mask:0xf
	s_waitcnt lgkmcnt(0)
	v_add_f32_e32 v2, v2, v35
	v_fmac_f32_e32 v14, 0xbb000000, v2
	v_fmac_f32_e32 v15, 0xbb000000, v2
	v_fmac_f32_e32 v18, 0xbb000000, v2
	v_mul_f32_e32 v14, v14, v14
	v_fmac_f32_e32 v20, 0xbb000000, v2
	v_mul_f32_e32 v15, v15, v15
	v_fmac_f32_e32 v14, v18, v18
	v_fmac_f32_e32 v15, v20, v20
	v_fmac_f32_e32 v16, 0xbb000000, v2
	v_add_f32_e32 v14, v14, v15
	v_fmac_f32_e32 v21, 0xbb000000, v2
	v_mul_f32_e32 v15, v16, v16
	v_fmac_f32_e32 v15, v21, v21
	v_fmac_f32_e32 v17, 0xbb000000, v2
	v_add_f32_e32 v14, v15, v14
	v_fmac_f32_e32 v22, 0xbb000000, v2
	v_mul_f32_e32 v15, v17, v17
	v_fmac_f32_e32 v10, 0xbb000000, v2
	v_fmac_f32_e32 v15, v22, v22
	v_fmac_f32_e32 v23, 0xbb000000, v2
	v_mul_f32_e32 v10, v10, v10
	v_fmac_f32_e32 v11, 0xbb000000, v2
	v_add_f32_e32 v14, v15, v14
	v_fmac_f32_e32 v10, v23, v23
	v_fmac_f32_e32 v24, 0xbb000000, v2
	v_mul_f32_e32 v11, v11, v11
	v_add_f32_e32 v10, v10, v14
	v_fmac_f32_e32 v11, v24, v24
	v_fmac_f32_e32 v12, 0xbb000000, v2
	v_add_f32_e32 v10, v11, v10
	v_fmac_f32_e32 v25, 0xbb000000, v2
	v_mul_f32_e32 v11, v12, v12
	v_fmac_f32_e32 v11, v25, v25
	v_fmac_f32_e32 v13, 0xbb000000, v2
	v_add_f32_e32 v10, v11, v10
	v_fmac_f32_e32 v26, 0xbb000000, v2
	v_mul_f32_e32 v11, v13, v13
	v_fmac_f32_e32 v6, 0xbb000000, v2
	v_fmac_f32_e32 v11, v26, v26
	v_fmac_f32_e32 v27, 0xbb000000, v2
	v_mul_f32_e32 v6, v6, v6
	v_fmac_f32_e32 v7, 0xbb000000, v2
	v_add_f32_e32 v10, v11, v10
	v_fmac_f32_e32 v6, v27, v27
	v_fmac_f32_e32 v28, 0xbb000000, v2
	v_mul_f32_e32 v7, v7, v7
	v_add_f32_e32 v6, v6, v10
	v_fmac_f32_e32 v7, v28, v28
	v_fmac_f32_e32 v8, 0xbb000000, v2
	v_add_f32_e32 v6, v7, v6
	v_fmac_f32_e32 v29, 0xbb000000, v2
	v_mul_f32_e32 v7, v8, v8
	v_fmac_f32_e32 v7, v29, v29
	v_fmac_f32_e32 v9, 0xbb000000, v2
	v_add_f32_e32 v6, v7, v6
	v_fmac_f32_e32 v30, 0xbb000000, v2
	v_mul_f32_e32 v7, v9, v9
	v_fmac_f32_e32 v7, v30, v30
	v_fmac_f32_e32 v32, 0xbb000000, v2
	v_add_f32_e32 v6, v7, v6
	v_fmac_f32_e32 v31, 0xbb000000, v2
	v_mul_f32_e32 v7, v32, v32
	v_fmac_f32_e32 v3, 0xbb000000, v2
	v_fmac_f32_e32 v7, v31, v31
	v_fmac_f32_e32 v19, 0xbb000000, v2
	v_mul_f32_e32 v3, v3, v3
	v_fmac_f32_e32 v4, 0xbb000000, v2
	v_add_f32_e32 v6, v7, v6
	v_fmac_f32_e32 v3, v19, v19
	v_fmac_f32_e32 v33, 0xbb000000, v2
	v_mul_f32_e32 v4, v4, v4
	v_add_f32_e32 v3, v3, v6
	v_fmac_f32_e32 v4, v33, v33
	v_fmac_f32_e32 v5, 0xbb000000, v2
	v_add_f32_e32 v3, v4, v3
	v_fmac_f32_e32 v34, 0xbb000000, v2
	v_mul_f32_e32 v4, v5, v5
	v_fmac_f32_e32 v4, v34, v34
	v_add_f32_e32 v3, v4, v3
	s_nop 1
	v_mov_b32_dpp v4, v3 quad_perm:[1,0,3,2] row_mask:0xf bank_mask:0xf
	s_waitcnt lgkmcnt(0)
	v_add_f32_e32 v3, v3, v4
	s_nop 1
	v_mov_b32_dpp v4, v3 quad_perm:[2,3,0,1] row_mask:0xf bank_mask:0xf
	s_waitcnt lgkmcnt(0)
	v_add_f32_e32 v3, v3, v4
	s_nop 1
	v_mov_b32_dpp v4, v3 row_half_mirror row_mask:0xf bank_mask:0xf
	s_waitcnt lgkmcnt(0)
	v_add_f32_e32 v3, v3, v4
	s_nop 1
	v_mov_b32_dpp v4, v3 row_mirror row_mask:0xf bank_mask:0xf
	s_and_saveexec_b64 s[4:5], vcc
	s_cbranch_execz .LBB0_786
	s_waitcnt lgkmcnt(0)
	v_add_f32_e32 v3, v3, v4
	v_mov_b32_e32 v4, s7
	v_fmac_f32_e32 v4, 0x3b000000, v3
	v_rsq_f32_e32 v3, v4
	v_mul_f32_e32 v2, 0x3b000000, v2
	ds_write_b64 v0, v[2:3] offset:768

.LBB0_918:
	v_lshlrev_b32_e32 v250, 16, v230
	v_and_b32_e32 v251, 0xffff0000, v230
	v_lshlrev_b32_e32 v230, 16, v231
	v_and_b32_e32 v231, 0xffff0000, v231
	v_lshlrev_b32_e32 v244, 16, v232
	v_and_b32_e32 v245, 0xffff0000, v232
	v_lshlrev_b32_e32 v232, 16, v233
	v_and_b32_e32 v233, 0xffff0000, v233
	v_pk_mul_f32 v[92:93], v[92:93], v[240:241]
	s_mov_b32 s4, 0x3fd744fd
	v_pk_mul_f32 v[84:85], v[84:85], v[236:237]
	v_pk_mul_f32 v[82:83], v[82:83], v[234:235]
	v_pk_mul_f32 v[90:91], v[90:91], v[238:239]
	v_pk_fma_f32 v[238:239], v[230:231], s[4:5], v[92:93] op_sel_hi:[1,0,1]
	v_pk_fma_f32 v[230:231], v[232:233], s[4:5], v[84:85] op_sel_hi:[1,0,1]
	v_pk_fma_f32 v[232:233], v[244:245], s[4:5], v[82:83] op_sel_hi:[1,0,1]
	v_lshlrev_b32_e32 v82, 16, v190
	v_and_b32_e32 v83, 0xffff0000, v190
	v_lshlrev_b32_e32 v84, 16, v191
	v_and_b32_e32 v85, 0xffff0000, v191
	v_pk_mul_f32 v[96:97], v[96:97], v[216:217]
	v_pk_mul_f32 v[94:95], v[94:95], v[214:215]
	v_pk_fma_f32 v[240:241], v[250:251], s[4:5], v[90:91] op_sel_hi:[1,0,1]
	v_lshlrev_b32_e32 v90, 16, v192
	v_and_b32_e32 v91, 0xffff0000, v192
	v_lshlrev_b32_e32 v92, 16, v193
	v_and_b32_e32 v93, 0xffff0000, v193
	v_pk_fma_f32 v[214:215], v[84:85], s[4:5], v[96:97] op_sel_hi:[1,0,1]
	v_pk_fma_f32 v[216:217], v[82:83], s[4:5], v[94:95] op_sel_hi:[1,0,1]
	v_pk_mul_f32 v[82:83], v[88:89], v[212:213]
	v_pk_mul_f32 v[84:85], v[86:87], v[210:211]
	v_pk_fma_f32 v[210:211], v[92:93], s[4:5], v[82:83] op_sel_hi:[1,0,1]
	v_pk_fma_f32 v[212:213], v[90:91], s[4:5], v[84:85] op_sel_hi:[1,0,1]
	v_pk_mov_b32 v[82:83], v[216:217], v[214:215] op_sel:[1,0]
	v_mov_b32_e32 v84, v216
	v_mov_b32_e32 v85, v215
	v_pk_add_f32 v[82:83], v[82:83], v[84:85]
	v_pk_mov_b32 v[84:85], v[212:213], v[210:211] op_sel:[1,0]
	v_mov_b32_e32 v86, v212
	v_mov_b32_e32 v87, v211
	v_pk_add_f32 v[84:85], v[84:85], v[86:87]
	v_add_f32_e32 v82, v82, v83
	v_pk_add_f32 v[84:85], v[84:85], v[84:85] op_sel:[0,1] op_sel_hi:[1,0]
	v_add_f32_e32 v82, 0, v82
	v_add_f32_e32 v86, v240, v241
	v_add_f32_e32 v88, v238, v239
	v_mov_b32_e32 v83, v232
	v_mov_b32_e32 v85, v233
	v_mov_b32_e32 v87, v230
	v_mov_b32_e32 v89, v231
	v_and_b32_e32 v0, 63, v252
	v_pk_add_f32 v[82:83], v[82:83], v[84:85]
	v_pk_add_f32 v[84:85], v[86:87], v[88:89]
	v_lshlrev_b32_e32 v90, 2, v0
	v_pk_add_f32 v[82:83], v[82:83], v[84:85]
	v_xor_b32_e32 v234, 64, v90
	v_add_f32_e32 v82, v82, v83
	v_mov_b32_e32 v83, v82
	s_nop 1
	v_permlane16_swap_b32_e32 v82, v83
	v_xor_b32_e32 v235, 0x80, v90
	v_readlane_b32 s4, v254, 11
	v_cmp_gt_u32_e32 vcc, 16, v0
	s_waitcnt lgkmcnt(0)
	v_add_f32_e32 v82, v82, v83
	v_mov_b32_e32 v83, v82
	s_nop 1
	v_permlane32_swap_b32_e32 v82, v83
	v_or_b32_e32 v236, s4, v253
	v_readlane_b32 s4, v254, 6
	s_waitcnt lgkmcnt(0)
	v_add_f32_e32 v83, v82, v83
	v_fmamk_f32 v84, v83, 0xbc800000, v215
	v_fmamk_f32 v86, v83, 0xbc800000, v217
	v_fmamk_f32 v82, v83, 0xbc800000, v214
	v_fmamk_f32 v85, v83, 0xbc800000, v216
	v_mul_f32_e32 v86, v86, v86
	v_mul_f32_e32 v84, v84, v84
	v_fmac_f32_e32 v86, v85, v85
	v_fmac_f32_e32 v84, v82, v82
	v_fmamk_f32 v85, v83, 0xbc800000, v211
	v_fmamk_f32 v87, v83, 0xbc800000, v213
	v_add_f32_e32 v82, v86, v84
	v_fmamk_f32 v84, v83, 0xbc800000, v210
	v_fmamk_f32 v86, v83, 0xbc800000, v212
	v_mul_f32_e32 v87, v87, v87
	v_mul_f32_e32 v85, v85, v85
	v_fmac_f32_e32 v87, v86, v86
	v_fmac_f32_e32 v85, v84, v84
	v_add_f32_e32 v84, v87, v85
	v_fmamk_f32 v85, v83, 0xbc800000, v239
	v_fmamk_f32 v87, v83, 0xbc800000, v241
	v_add_f32_e32 v82, v82, v84
	v_fmamk_f32 v84, v83, 0xbc800000, v238
	v_fmamk_f32 v86, v83, 0xbc800000, v240
	v_mul_f32_e32 v87, v87, v87
	v_mul_f32_e32 v85, v85, v85
	v_fmac_f32_e32 v87, v86, v86
	v_fmac_f32_e32 v85, v84, v84
	v_add_f32_e32 v84, v87, v85
	v_fmamk_f32 v85, v83, 0xbc800000, v231
	v_fmamk_f32 v87, v83, 0xbc800000, v233
	v_add_f32_e32 v82, v84, v82
	v_fmamk_f32 v84, v83, 0xbc800000, v230
	v_fmamk_f32 v86, v83, 0xbc800000, v232
	v_mul_f32_e32 v87, v87, v87
	v_mul_f32_e32 v85, v85, v85
	v_fmac_f32_e32 v87, v86, v86
	v_fmac_f32_e32 v85, v84, v84
	v_add_f32_e32 v84, v87, v85
	v_add_f32_e32 v82, v84, v82
	v_mov_b32_e32 v84, v82
	s_nop 1
	v_permlane16_swap_b32_e32 v82, v84
	s_waitcnt lgkmcnt(0)
	v_add_f32_e32 v84, v82, v84
	v_mov_b32_e32 v85, v84
	s_nop 1
	v_permlane32_swap_b32_e32 v84, v85
	v_lshl_add_u32 v82, v236, 5, s4
	s_and_saveexec_b64 s[4:5], vcc
	s_cbranch_execz .LBB0_920
	v_mul_f32_e32 v86, 0x3c800000, v83
	s_waitcnt lgkmcnt(0)
	v_add_f32_e32 v87, v84, v85
	ds_write_b64 v82, v[86:87]
.LBB0_920:
	s_or_b64 exec, exec, s[4:5]
	v_lshlrev_b32_e32 v88, 16, v220
	v_and_b32_e32 v89, 0xffff0000, v220
	v_lshlrev_b32_e32 v90, 16, v221
	v_and_b32_e32 v91, 0xffff0000, v221
	s_mov_b32 s4, 0x3fd744fd
	v_pk_mul_f32 v[68:69], v[68:69], v[224:225]
	v_pk_mul_f32 v[66:67], v[66:67], v[222:223]
	v_lshlrev_b32_e32 v84, 16, v218
	s_waitcnt lgkmcnt(0)
	v_and_b32_e32 v85, 0xffff0000, v218
	v_lshlrev_b32_e32 v86, 16, v219
	v_and_b32_e32 v87, 0xffff0000, v219
	v_pk_mul_f32 v[76:77], v[76:77], v[228:229]
	v_pk_mul_f32 v[74:75], v[74:75], v[226:227]
	v_pk_fma_f32 v[92:93], v[90:91], s[4:5], v[68:69] op_sel_hi:[1,0,1]
	v_pk_fma_f32 v[94:95], v[88:89], s[4:5], v[66:67] op_sel_hi:[1,0,1]
	v_lshlrev_b32_e32 v66, 16, v162
	v_and_b32_e32 v67, 0xffff0000, v162
	v_lshlrev_b32_e32 v68, 16, v163
	v_and_b32_e32 v69, 0xffff0000, v163
	v_pk_mul_f32 v[80:81], v[80:81], v[196:197]
	v_pk_mul_f32 v[78:79], v[78:79], v[194:195]
	v_pk_fma_f32 v[96:97], v[86:87], s[4:5], v[76:77] op_sel_hi:[1,0,1]
	v_pk_fma_f32 v[190:191], v[84:85], s[4:5], v[74:75] op_sel_hi:[1,0,1]
	v_lshlrev_b32_e32 v74, 16, v164
	v_and_b32_e32 v75, 0xffff0000, v164
	v_lshlrev_b32_e32 v76, 16, v165
	v_and_b32_e32 v77, 0xffff0000, v165
	v_pk_fma_f32 v[192:193], v[68:69], s[4:5], v[80:81] op_sel_hi:[1,0,1]
	v_pk_fma_f32 v[194:195], v[66:67], s[4:5], v[78:79] op_sel_hi:[1,0,1]
	v_pk_mul_f32 v[66:67], v[72:73], v[188:189]
	v_pk_mul_f32 v[68:69], v[70:71], v[186:187]
	v_pk_fma_f32 v[186:187], v[76:77], s[4:5], v[66:67] op_sel_hi:[1,0,1]
	v_pk_fma_f32 v[188:189], v[74:75], s[4:5], v[68:69] op_sel_hi:[1,0,1]
	v_pk_mov_b32 v[66:67], v[194:195], v[192:193] op_sel:[1,0]
	v_mov_b32_e32 v68, v194
	v_mov_b32_e32 v69, v193
	v_pk_add_f32 v[66:67], v[66:67], v[68:69]
	v_pk_mov_b32 v[68:69], v[188:189], v[186:187] op_sel:[1,0]
	v_mov_b32_e32 v70, v188
	v_mov_b32_e32 v71, v187
	v_pk_add_f32 v[68:69], v[68:69], v[70:71]
	v_add_f32_e32 v66, v66, v67
	v_pk_add_f32 v[68:69], v[68:69], v[68:69] op_sel_hi:[0,1]
	v_add_f32_e32 v67, 0, v66
	v_add_f32_e32 v71, v190, v191
	v_add_f32_e32 v73, v96, v97
	v_mov_b32_e32 v68, v94
	v_mov_b32_e32 v66, v95
	v_mov_b32_e32 v70, v92
	v_mov_b32_e32 v72, v93
	v_pk_add_f32 v[66:67], v[68:69], v[66:67]
	v_pk_add_f32 v[68:69], v[70:71], v[72:73]
	s_nop 0
	v_pk_add_f32 v[66:67], v[66:67], v[68:69]
	s_nop 0
	v_add_f32_e32 v66, v66, v67
	v_mov_b32_e32 v67, v66
	s_nop 1
	v_permlane16_swap_b32_e32 v66, v67
	s_waitcnt lgkmcnt(0)
	v_add_f32_e32 v66, v66, v67
	v_mov_b32_e32 v67, v66
	s_nop 1
	v_permlane32_swap_b32_e32 v66, v67
	s_waitcnt lgkmcnt(0)
	v_add_f32_e32 v66, v66, v67
	v_fmamk_f32 v68, v66, 0xbc800000, v193
	v_fmamk_f32 v70, v66, 0xbc800000, v195
	v_fmamk_f32 v67, v66, 0xbc800000, v192
	v_fmamk_f32 v69, v66, 0xbc800000, v194
	v_mul_f32_e32 v70, v70, v70
	v_mul_f32_e32 v68, v68, v68
	v_fmac_f32_e32 v70, v69, v69
	v_fmac_f32_e32 v68, v67, v67
	v_fmamk_f32 v69, v66, 0xbc800000, v187
	v_fmamk_f32 v71, v66, 0xbc800000, v189
	v_add_f32_e32 v67, v70, v68
	v_fmamk_f32 v68, v66, 0xbc800000, v186
	v_fmamk_f32 v70, v66, 0xbc800000, v188
	v_mul_f32_e32 v71, v71, v71
	v_mul_f32_e32 v69, v69, v69
	v_fmac_f32_e32 v71, v70, v70
	v_fmac_f32_e32 v69, v68, v68
	v_add_f32_e32 v68, v71, v69
	v_fmamk_f32 v69, v66, 0xbc800000, v97
	v_fmamk_f32 v71, v66, 0xbc800000, v191
	v_add_f32_e32 v67, v67, v68
	v_fmamk_f32 v68, v66, 0xbc800000, v96
	v_fmamk_f32 v70, v66, 0xbc800000, v190
	v_mul_f32_e32 v71, v71, v71
	v_mul_f32_e32 v69, v69, v69
	v_fmac_f32_e32 v71, v70, v70
	v_fmac_f32_e32 v69, v68, v68
	v_add_f32_e32 v68, v71, v69
	v_fmamk_f32 v69, v66, 0xbc800000, v93
	v_fmamk_f32 v71, v66, 0xbc800000, v95
	v_add_f32_e32 v67, v68, v67
	v_fmamk_f32 v68, v66, 0xbc800000, v92
	v_fmamk_f32 v70, v66, 0xbc800000, v94
	v_mul_f32_e32 v71, v71, v71
	v_mul_f32_e32 v69, v69, v69
	v_fmac_f32_e32 v71, v70, v70
	v_fmac_f32_e32 v69, v68, v68
	v_add_f32_e32 v68, v71, v69
	v_add_f32_e32 v67, v68, v67
	v_mov_b32_e32 v68, v67
	s_nop 1
	v_permlane16_swap_b32_e32 v67, v68
	s_waitcnt lgkmcnt(0)
	v_add_f32_e32 v67, v67, v68
	v_mov_b32_e32 v68, v67
	s_nop 1
	v_permlane32_swap_b32_e32 v67, v68
	s_and_saveexec_b64 s[4:5], vcc
	s_cbranch_execz .LBB0_922
	v_mul_f32_e32 v66, 0x3c800000, v66
	s_waitcnt lgkmcnt(0)
	v_add_f32_e32 v67, v67, v68
	ds_write_b64 v82, v[66:67] offset:512
.LBB0_922:
	s_or_b64 exec, exec, s[4:5]
	v_lshlrev_b32_e32 v70, 16, v200
	v_and_b32_e32 v71, 0xffff0000, v200
	v_lshlrev_b32_e32 v72, 16, v201
	v_and_b32_e32 v73, 0xffff0000, v201
	s_mov_b32 s4, 0x3fd744fd
	v_pk_mul_f32 v[52:53], v[52:53], v[204:205]
	v_pk_mul_f32 v[50:51], v[50:51], v[202:203]
	v_lshlrev_b32_e32 v66, 16, v198
	v_and_b32_e32 v67, 0xffff0000, v198
	s_waitcnt lgkmcnt(0)
	v_lshlrev_b32_e32 v68, 16, v199
	v_and_b32_e32 v69, 0xffff0000, v199
	v_pk_mul_f32 v[60:61], v[60:61], v[208:209]
	v_pk_mul_f32 v[58:59], v[58:59], v[206:207]
	v_pk_fma_f32 v[84:85], v[72:73], s[4:5], v[52:53] op_sel_hi:[1,0,1]
	v_pk_fma_f32 v[86:87], v[70:71], s[4:5], v[50:51] op_sel_hi:[1,0,1]
	v_lshlrev_b32_e32 v50, 16, v138
	v_and_b32_e32 v51, 0xffff0000, v138
	v_lshlrev_b32_e32 v52, 16, v139
	v_and_b32_e32 v53, 0xffff0000, v139
	v_pk_mul_f32 v[64:65], v[64:65], v[176:177]
	v_pk_mul_f32 v[62:63], v[62:63], v[174:175]
	v_pk_fma_f32 v[88:89], v[68:69], s[4:5], v[60:61] op_sel_hi:[1,0,1]
	v_pk_fma_f32 v[90:91], v[66:67], s[4:5], v[58:59] op_sel_hi:[1,0,1]
	v_lshlrev_b32_e32 v58, 16, v140
	v_and_b32_e32 v59, 0xffff0000, v140
	v_lshlrev_b32_e32 v60, 16, v141
	v_and_b32_e32 v61, 0xffff0000, v141
	v_pk_fma_f32 v[174:175], v[52:53], s[4:5], v[64:65] op_sel_hi:[1,0,1]
	v_pk_fma_f32 v[176:177], v[50:51], s[4:5], v[62:63] op_sel_hi:[1,0,1]
	v_pk_mul_f32 v[50:51], v[56:57], v[168:169]
	v_pk_mul_f32 v[52:53], v[54:55], v[166:167]
	v_pk_fma_f32 v[162:163], v[60:61], s[4:5], v[50:51] op_sel_hi:[1,0,1]
	v_pk_fma_f32 v[164:165], v[58:59], s[4:5], v[52:53] op_sel_hi:[1,0,1]
	v_pk_mov_b32 v[50:51], v[176:177], v[174:175] op_sel:[1,0]
	v_mov_b32_e32 v52, v176
	v_mov_b32_e32 v53, v175
	v_pk_add_f32 v[50:51], v[50:51], v[52:53]
	v_pk_mov_b32 v[52:53], v[164:165], v[162:163] op_sel:[1,0]
	v_mov_b32_e32 v54, v164
	v_mov_b32_e32 v55, v163
	v_pk_add_f32 v[52:53], v[52:53], v[54:55]
	v_add_f32_e32 v50, v50, v51
	v_pk_add_f32 v[52:53], v[52:53], v[52:53] op_sel_hi:[0,1]
	v_add_f32_e32 v51, 0, v50
	v_add_f32_e32 v55, v90, v91
	v_add_f32_e32 v57, v88, v89
	v_mov_b32_e32 v52, v86
	v_mov_b32_e32 v50, v87
	v_mov_b32_e32 v54, v84
	v_mov_b32_e32 v56, v85
	v_pk_add_f32 v[50:51], v[52:53], v[50:51]
	v_pk_add_f32 v[52:53], v[54:55], v[56:57]
	s_nop 0
	v_pk_add_f32 v[50:51], v[50:51], v[52:53]
	s_nop 0
	v_add_f32_e32 v50, v50, v51
	v_mov_b32_e32 v51, v50
	s_nop 1
	v_permlane16_swap_b32_e32 v50, v51
	s_waitcnt lgkmcnt(0)
	v_add_f32_e32 v50, v50, v51
	v_mov_b32_e32 v51, v50
	s_nop 1
	v_permlane32_swap_b32_e32 v50, v51
	s_waitcnt lgkmcnt(0)
	v_add_f32_e32 v50, v50, v51
	v_fmamk_f32 v52, v50, 0xbc800000, v175
	v_fmamk_f32 v54, v50, 0xbc800000, v177
	v_fmamk_f32 v51, v50, 0xbc800000, v174
	v_fmamk_f32 v53, v50, 0xbc800000, v176
	v_mul_f32_e32 v54, v54, v54
	v_mul_f32_e32 v52, v52, v52
	v_fmac_f32_e32 v54, v53, v53
	v_fmac_f32_e32 v52, v51, v51
	v_fmamk_f32 v53, v50, 0xbc800000, v163
	v_fmamk_f32 v55, v50, 0xbc800000, v165
	v_add_f32_e32 v51, v54, v52
	v_fmamk_f32 v52, v50, 0xbc800000, v162
	v_fmamk_f32 v54, v50, 0xbc800000, v164
	v_mul_f32_e32 v55, v55, v55
	v_mul_f32_e32 v53, v53, v53
	v_fmac_f32_e32 v55, v54, v54
	v_fmac_f32_e32 v53, v52, v52
	v_add_f32_e32 v52, v55, v53
	v_fmamk_f32 v53, v50, 0xbc800000, v89
	v_fmamk_f32 v55, v50, 0xbc800000, v91
	v_add_f32_e32 v51, v51, v52
	v_fmamk_f32 v52, v50, 0xbc800000, v88
	v_fmamk_f32 v54, v50, 0xbc800000, v90
	v_mul_f32_e32 v55, v55, v55
	v_mul_f32_e32 v53, v53, v53
	v_fmac_f32_e32 v55, v54, v54
	v_fmac_f32_e32 v53, v52, v52
	v_add_f32_e32 v52, v55, v53
	v_fmamk_f32 v53, v50, 0xbc800000, v85
	v_fmamk_f32 v55, v50, 0xbc800000, v87
	v_add_f32_e32 v51, v52, v51
	v_fmamk_f32 v52, v50, 0xbc800000, v84
	v_fmamk_f32 v54, v50, 0xbc800000, v86
	v_mul_f32_e32 v55, v55, v55
	v_mul_f32_e32 v53, v53, v53
	v_fmac_f32_e32 v55, v54, v54
	v_fmac_f32_e32 v53, v52, v52
	v_add_f32_e32 v52, v55, v53
	v_add_f32_e32 v51, v52, v51
	v_mov_b32_e32 v52, v51
	s_nop 1
	v_permlane16_swap_b32_e32 v51, v52
	s_waitcnt lgkmcnt(0)
	v_add_f32_e32 v51, v51, v52
	v_mov_b32_e32 v52, v51
	s_nop 1
	v_permlane32_swap_b32_e32 v51, v52
	s_and_saveexec_b64 s[4:5], vcc
	s_cbranch_execz .LBB0_924
	v_mul_f32_e32 v50, 0x3c800000, v50
	s_waitcnt lgkmcnt(0)
	v_add_f32_e32 v51, v51, v52
	ds_write_b64 v82, v[50:51] offset:1024
.LBB0_924:
	s_or_b64 exec, exec, s[4:5]
	v_lshlrev_b32_e32 v54, 16, v172
	v_and_b32_e32 v55, 0xffff0000, v172
	v_lshlrev_b32_e32 v56, 16, v173
	v_and_b32_e32 v57, 0xffff0000, v173
	s_mov_b32 s4, 0x3fd744fd
	v_pk_mul_f32 v[36:37], v[36:37], v[180:181]
	v_pk_mul_f32 v[34:35], v[34:35], v[178:179]
	v_lshlrev_b32_e32 v50, 16, v170
	v_and_b32_e32 v51, 0xffff0000, v170
	s_waitcnt lgkmcnt(0)
	v_lshlrev_b32_e32 v52, 16, v171
	v_and_b32_e32 v53, 0xffff0000, v171
	v_pk_mul_f32 v[44:45], v[44:45], v[184:185]
	v_pk_mul_f32 v[42:43], v[42:43], v[182:183]
	v_pk_fma_f32 v[76:77], v[56:57], s[4:5], v[36:37] op_sel_hi:[1,0,1]
	v_pk_fma_f32 v[78:79], v[54:55], s[4:5], v[34:35] op_sel_hi:[1,0,1]
	v_lshlrev_b32_e32 v34, 16, v114
	v_and_b32_e32 v35, 0xffff0000, v114
	v_lshlrev_b32_e32 v36, 16, v115
	v_and_b32_e32 v37, 0xffff0000, v115
	v_pk_mul_f32 v[48:49], v[48:49], v[152:153]
	v_pk_mul_f32 v[46:47], v[46:47], v[150:151]
	v_pk_fma_f32 v[80:81], v[52:53], s[4:5], v[44:45] op_sel_hi:[1,0,1]
	v_pk_fma_f32 v[82:83], v[50:51], s[4:5], v[42:43] op_sel_hi:[1,0,1]
	v_lshlrev_b32_e32 v42, 16, v116
	v_and_b32_e32 v43, 0xffff0000, v116
	v_lshlrev_b32_e32 v44, 16, v117
	v_and_b32_e32 v45, 0xffff0000, v117
	v_pk_fma_f32 v[150:151], v[36:37], s[4:5], v[48:49] op_sel_hi:[1,0,1]
	v_pk_fma_f32 v[152:153], v[34:35], s[4:5], v[46:47] op_sel_hi:[1,0,1]
	v_pk_mul_f32 v[34:35], v[40:41], v[148:149]
	v_pk_mul_f32 v[36:37], v[38:39], v[146:147]
	v_pk_fma_f32 v[138:139], v[44:45], s[4:5], v[34:35] op_sel_hi:[1,0,1]
	v_pk_fma_f32 v[140:141], v[42:43], s[4:5], v[36:37] op_sel_hi:[1,0,1]
	v_pk_mov_b32 v[34:35], v[152:153], v[150:151] op_sel:[1,0]
	v_mov_b32_e32 v36, v152
	v_mov_b32_e32 v37, v151
	v_pk_add_f32 v[34:35], v[34:35], v[36:37]
	v_pk_mov_b32 v[36:37], v[140:141], v[138:139] op_sel:[1,0]
	v_mov_b32_e32 v38, v140
	v_mov_b32_e32 v39, v139
	v_pk_add_f32 v[36:37], v[36:37], v[38:39]
	v_add_f32_e32 v34, v34, v35
	v_pk_add_f32 v[36:37], v[36:37], v[36:37] op_sel_hi:[0,1]
	v_add_f32_e32 v35, 0, v34
	v_add_f32_e32 v39, v82, v83
	v_add_f32_e32 v41, v80, v81
	v_mov_b32_e32 v36, v78
	v_mov_b32_e32 v34, v79
	v_mov_b32_e32 v38, v76
	v_mov_b32_e32 v40, v77
	v_pk_add_f32 v[34:35], v[36:37], v[34:35]
	v_pk_add_f32 v[36:37], v[38:39], v[40:41]
	v_readlane_b32 s4, v254, 6
	v_pk_add_f32 v[34:35], v[34:35], v[36:37]
	s_nop 0
	v_add_f32_e32 v34, v34, v35
	v_mov_b32_e32 v35, v34
	s_nop 1
	v_permlane16_swap_b32_e32 v34, v35
	s_waitcnt lgkmcnt(0)
	v_add_f32_e32 v34, v34, v35
	v_mov_b32_e32 v35, v34
	s_nop 1
	v_permlane32_swap_b32_e32 v34, v35
	s_waitcnt lgkmcnt(0)
	v_add_f32_e32 v35, v34, v35
	v_fmamk_f32 v36, v35, 0xbc800000, v151
	v_fmamk_f32 v38, v35, 0xbc800000, v153
	v_fmamk_f32 v34, v35, 0xbc800000, v150
	v_fmamk_f32 v37, v35, 0xbc800000, v152
	v_mul_f32_e32 v38, v38, v38
	v_mul_f32_e32 v36, v36, v36
	v_fmac_f32_e32 v38, v37, v37
	v_fmac_f32_e32 v36, v34, v34
	v_fmamk_f32 v37, v35, 0xbc800000, v139
	v_fmamk_f32 v39, v35, 0xbc800000, v141
	v_add_f32_e32 v34, v38, v36
	v_fmamk_f32 v36, v35, 0xbc800000, v138
	v_fmamk_f32 v38, v35, 0xbc800000, v140
	v_mul_f32_e32 v39, v39, v39
	v_mul_f32_e32 v37, v37, v37
	v_fmac_f32_e32 v39, v38, v38
	v_fmac_f32_e32 v37, v36, v36
	v_add_f32_e32 v36, v39, v37
	v_fmamk_f32 v37, v35, 0xbc800000, v81
	v_fmamk_f32 v39, v35, 0xbc800000, v83
	v_add_f32_e32 v34, v34, v36
	v_fmamk_f32 v36, v35, 0xbc800000, v80
	v_fmamk_f32 v38, v35, 0xbc800000, v82
	v_mul_f32_e32 v39, v39, v39
	v_mul_f32_e32 v37, v37, v37
	v_fmac_f32_e32 v39, v38, v38
	v_fmac_f32_e32 v37, v36, v36
	v_add_f32_e32 v36, v39, v37
	v_fmamk_f32 v37, v35, 0xbc800000, v77
	v_fmamk_f32 v39, v35, 0xbc800000, v79
	v_add_f32_e32 v34, v36, v34
	v_fmamk_f32 v36, v35, 0xbc800000, v76
	v_fmamk_f32 v38, v35, 0xbc800000, v78
	v_mul_f32_e32 v39, v39, v39
	v_mul_f32_e32 v37, v37, v37
	v_fmac_f32_e32 v39, v38, v38
	v_fmac_f32_e32 v37, v36, v36
	v_add_f32_e32 v36, v39, v37
	v_add_f32_e32 v34, v36, v34
	v_mov_b32_e32 v36, v34
	s_nop 1
	v_permlane16_swap_b32_e32 v34, v36
	s_waitcnt lgkmcnt(0)
	v_add_f32_e32 v36, v34, v36
	v_mov_b32_e32 v37, v36
	s_nop 1
	v_permlane32_swap_b32_e32 v36, v37
	v_add_u32_e32 v34, 0x60, v236
	v_lshl_add_u32 v34, v34, 5, s4
	s_and_saveexec_b64 s[4:5], vcc
	s_cbranch_execz .LBB0_926
	v_mul_f32_e32 v38, 0x3c800000, v35
	s_waitcnt lgkmcnt(0)
	v_add_f32_e32 v39, v36, v37
	ds_write_b64 v34, v[38:39]
.LBB0_926:
	s_or_b64 exec, exec, s[4:5]
	v_lshlrev_b32_e32 v40, 16, v144
	v_and_b32_e32 v41, 0xffff0000, v144
	v_lshlrev_b32_e32 v42, 16, v145
	v_and_b32_e32 v43, 0xffff0000, v145
	s_mov_b32 s4, 0x3fd744fd
	v_pk_mul_f32 v[20:21], v[20:21], v[156:157]
	v_pk_mul_f32 v[18:19], v[18:19], v[154:155]
	v_lshlrev_b32_e32 v36, 16, v142
	s_waitcnt lgkmcnt(0)
	v_and_b32_e32 v37, 0xffff0000, v142
	v_lshlrev_b32_e32 v38, 16, v143
	v_and_b32_e32 v39, 0xffff0000, v143
	v_pk_mul_f32 v[28:29], v[28:29], v[160:161]
	v_pk_mul_f32 v[26:27], v[26:27], v[158:159]
	v_pk_fma_f32 v[68:69], v[42:43], s[4:5], v[20:21] op_sel_hi:[1,0,1]
	v_pk_fma_f32 v[70:71], v[40:41], s[4:5], v[18:19] op_sel_hi:[1,0,1]
	v_lshlrev_b32_e32 v18, 16, v102
	v_and_b32_e32 v19, 0xffff0000, v102
	v_lshlrev_b32_e32 v20, 16, v103
	v_and_b32_e32 v21, 0xffff0000, v103
	v_pk_mul_f32 v[32:33], v[32:33], v[128:129]
	v_pk_mul_f32 v[30:31], v[30:31], v[126:127]
	v_pk_fma_f32 v[72:73], v[38:39], s[4:5], v[28:29] op_sel_hi:[1,0,1]
	v_pk_fma_f32 v[74:75], v[36:37], s[4:5], v[26:27] op_sel_hi:[1,0,1]
	v_lshlrev_b32_e32 v26, 16, v104
	v_and_b32_e32 v27, 0xffff0000, v104
	v_lshlrev_b32_e32 v28, 16, v105
	v_and_b32_e32 v29, 0xffff0000, v105
	v_pk_fma_f32 v[126:127], v[20:21], s[4:5], v[32:33] op_sel_hi:[1,0,1]
	v_pk_fma_f32 v[128:129], v[18:19], s[4:5], v[30:31] op_sel_hi:[1,0,1]
	v_pk_mul_f32 v[18:19], v[24:25], v[124:125]
	v_pk_mul_f32 v[20:21], v[22:23], v[122:123]
	v_pk_fma_f32 v[114:115], v[28:29], s[4:5], v[18:19] op_sel_hi:[1,0,1]
	v_pk_fma_f32 v[116:117], v[26:27], s[4:5], v[20:21] op_sel_hi:[1,0,1]
	v_pk_mov_b32 v[18:19], v[128:129], v[126:127] op_sel:[1,0]
	v_mov_b32_e32 v20, v128
	v_mov_b32_e32 v21, v127
	v_pk_add_f32 v[18:19], v[18:19], v[20:21]
	v_pk_mov_b32 v[20:21], v[116:117], v[114:115] op_sel:[1,0]
	v_mov_b32_e32 v22, v116
	v_mov_b32_e32 v23, v115
	v_pk_add_f32 v[20:21], v[20:21], v[22:23]
	v_add_f32_e32 v18, v18, v19
	v_pk_add_f32 v[20:21], v[20:21], v[20:21] op_sel_hi:[0,1]
	v_add_f32_e32 v19, 0, v18
	v_add_f32_e32 v23, v74, v75
	v_add_f32_e32 v25, v72, v73
	v_mov_b32_e32 v20, v70
	v_mov_b32_e32 v18, v71
	v_mov_b32_e32 v22, v68
	v_mov_b32_e32 v24, v69
	v_pk_add_f32 v[18:19], v[20:21], v[18:19]
	v_pk_add_f32 v[20:21], v[22:23], v[24:25]
	s_nop 0
	v_pk_add_f32 v[18:19], v[18:19], v[20:21]
	s_nop 0
	v_add_f32_e32 v18, v18, v19
	v_mov_b32_e32 v19, v18
	s_nop 1
	v_permlane16_swap_b32_e32 v18, v19
	s_waitcnt lgkmcnt(0)
	v_add_f32_e32 v18, v18, v19
	v_mov_b32_e32 v19, v18
	s_nop 1
	v_permlane32_swap_b32_e32 v18, v19
	s_waitcnt lgkmcnt(0)
	v_add_f32_e32 v18, v18, v19
	v_fmamk_f32 v20, v18, 0xbc800000, v127
	v_fmamk_f32 v22, v18, 0xbc800000, v129
	v_fmamk_f32 v19, v18, 0xbc800000, v126
	v_fmamk_f32 v21, v18, 0xbc800000, v128
	v_mul_f32_e32 v22, v22, v22
	v_mul_f32_e32 v20, v20, v20
	v_fmac_f32_e32 v22, v21, v21
	v_fmac_f32_e32 v20, v19, v19
	v_fmamk_f32 v21, v18, 0xbc800000, v115
	v_fmamk_f32 v23, v18, 0xbc800000, v117
	v_add_f32_e32 v19, v22, v20
	v_fmamk_f32 v20, v18, 0xbc800000, v114
	v_fmamk_f32 v22, v18, 0xbc800000, v116
	v_mul_f32_e32 v23, v23, v23
	v_mul_f32_e32 v21, v21, v21
	v_fmac_f32_e32 v23, v22, v22
	v_fmac_f32_e32 v21, v20, v20
	v_add_f32_e32 v20, v23, v21
	v_fmamk_f32 v21, v18, 0xbc800000, v73
	v_fmamk_f32 v23, v18, 0xbc800000, v75
	v_add_f32_e32 v19, v19, v20
	v_fmamk_f32 v20, v18, 0xbc800000, v72
	v_fmamk_f32 v22, v18, 0xbc800000, v74
	v_mul_f32_e32 v23, v23, v23
	v_mul_f32_e32 v21, v21, v21
	v_fmac_f32_e32 v23, v22, v22
	v_fmac_f32_e32 v21, v20, v20
	v_add_f32_e32 v20, v23, v21
	v_fmamk_f32 v21, v18, 0xbc800000, v69
	v_fmamk_f32 v23, v18, 0xbc800000, v71
	v_add_f32_e32 v19, v20, v19
	v_fmamk_f32 v20, v18, 0xbc800000, v68
	v_fmamk_f32 v22, v18, 0xbc800000, v70
	v_mul_f32_e32 v23, v23, v23
	v_mul_f32_e32 v21, v21, v21
	v_fmac_f32_e32 v23, v22, v22
	v_fmac_f32_e32 v21, v20, v20
	v_add_f32_e32 v20, v23, v21
	v_add_f32_e32 v19, v20, v19
	v_mov_b32_e32 v20, v19
	s_nop 1
	v_permlane16_swap_b32_e32 v19, v20
	s_waitcnt lgkmcnt(0)
	v_add_f32_e32 v19, v19, v20
	v_mov_b32_e32 v20, v19
	s_nop 1
	v_permlane32_swap_b32_e32 v19, v20
	s_and_saveexec_b64 s[4:5], vcc
	s_cbranch_execz .LBB0_928
	v_mul_f32_e32 v18, 0x3c800000, v18
	s_waitcnt lgkmcnt(0)
	v_add_f32_e32 v19, v19, v20
	ds_write_b64 v34, v[18:19] offset:512
.LBB0_928:
	s_or_b64 exec, exec, s[4:5]
	v_lshlrev_b32_e32 v22, 16, v120
	v_and_b32_e32 v23, 0xffff0000, v120
	v_lshlrev_b32_e32 v24, 16, v121
	v_and_b32_e32 v25, 0xffff0000, v121
	s_mov_b32 s4, 0x3fd744fd
	s_waitcnt vmcnt(0)
	v_pk_mul_f32 v[4:5], v[4:5], v[132:133]
	v_pk_mul_f32 v[2:3], v[2:3], v[130:131]
	v_lshlrev_b32_e32 v18, 16, v118
	v_and_b32_e32 v19, 0xffff0000, v118
	s_waitcnt lgkmcnt(0)
	v_lshlrev_b32_e32 v20, 16, v119
	v_and_b32_e32 v21, 0xffff0000, v119
	v_pk_mul_f32 v[12:13], v[12:13], v[136:137]
	v_pk_mul_f32 v[10:11], v[10:11], v[134:135]
	v_pk_fma_f32 v[60:61], v[24:25], s[4:5], v[4:5] op_sel_hi:[1,0,1]
	v_pk_fma_f32 v[62:63], v[22:23], s[4:5], v[2:3] op_sel_hi:[1,0,1]
	v_lshlrev_b32_e32 v2, 16, v98
	v_and_b32_e32 v3, 0xffff0000, v98
	v_lshlrev_b32_e32 v4, 16, v99
	v_and_b32_e32 v5, 0xffff0000, v99
	v_pk_mul_f32 v[16:17], v[16:17], v[112:113]
	v_pk_mul_f32 v[14:15], v[14:15], v[110:111]
	v_pk_fma_f32 v[64:65], v[20:21], s[4:5], v[12:13] op_sel_hi:[1,0,1]
	v_pk_fma_f32 v[66:67], v[18:19], s[4:5], v[10:11] op_sel_hi:[1,0,1]
	v_lshlrev_b32_e32 v10, 16, v100
	v_and_b32_e32 v11, 0xffff0000, v100
	v_lshlrev_b32_e32 v12, 16, v101
	v_and_b32_e32 v13, 0xffff0000, v101
	v_pk_fma_f32 v[102:103], v[4:5], s[4:5], v[16:17] op_sel_hi:[1,0,1]
	v_pk_fma_f32 v[104:105], v[2:3], s[4:5], v[14:15] op_sel_hi:[1,0,1]
	v_pk_mul_f32 v[2:3], v[8:9], v[108:109]
	v_pk_mul_f32 v[4:5], v[6:7], v[106:107]
	v_pk_fma_f32 v[98:99], v[12:13], s[4:5], v[2:3] op_sel_hi:[1,0,1]
	v_pk_fma_f32 v[100:101], v[10:11], s[4:5], v[4:5] op_sel_hi:[1,0,1]
	v_pk_mov_b32 v[2:3], v[104:105], v[102:103] op_sel:[1,0]
	v_mov_b32_e32 v4, v104
	v_mov_b32_e32 v5, v103
	v_pk_add_f32 v[2:3], v[2:3], v[4:5]
	v_pk_mov_b32 v[4:5], v[100:101], v[98:99] op_sel:[1,0]
	v_mov_b32_e32 v6, v100
	v_mov_b32_e32 v7, v99
	v_pk_add_f32 v[4:5], v[4:5], v[6:7]
	v_add_f32_e32 v2, v2, v3
	v_pk_add_f32 v[4:5], v[4:5], v[4:5] op_sel_hi:[0,1]
	v_add_f32_e32 v3, 0, v2
	v_add_f32_e32 v7, v66, v67
	v_add_f32_e32 v9, v64, v65
	v_mov_b32_e32 v4, v62
	v_mov_b32_e32 v2, v63
	v_mov_b32_e32 v6, v60
	v_mov_b32_e32 v8, v61
	v_pk_add_f32 v[2:3], v[4:5], v[2:3]
	v_pk_add_f32 v[4:5], v[6:7], v[8:9]
	s_nop 0
	v_pk_add_f32 v[2:3], v[2:3], v[4:5]
	s_nop 0
	v_add_f32_e32 v2, v2, v3
	v_mov_b32_e32 v3, v2
	s_nop 1
	v_permlane16_swap_b32_e32 v2, v3
	s_waitcnt lgkmcnt(0)
	v_add_f32_e32 v2, v2, v3
	v_mov_b32_e32 v3, v2
	s_nop 1
	v_permlane32_swap_b32_e32 v2, v3
	s_waitcnt lgkmcnt(0)
	v_add_f32_e32 v2, v2, v3
	v_fmamk_f32 v4, v2, 0xbc800000, v103
	v_fmamk_f32 v6, v2, 0xbc800000, v105
	v_fmamk_f32 v3, v2, 0xbc800000, v102
	v_fmamk_f32 v5, v2, 0xbc800000, v104
	v_mul_f32_e32 v6, v6, v6
	v_mul_f32_e32 v4, v4, v4
	v_fmac_f32_e32 v6, v5, v5
	v_fmac_f32_e32 v4, v3, v3
	v_fmamk_f32 v5, v2, 0xbc800000, v99
	v_fmamk_f32 v7, v2, 0xbc800000, v101
	v_add_f32_e32 v3, v6, v4
	v_fmamk_f32 v4, v2, 0xbc800000, v98
	v_fmamk_f32 v6, v2, 0xbc800000, v100
	v_mul_f32_e32 v7, v7, v7
	v_mul_f32_e32 v5, v5, v5
	v_fmac_f32_e32 v7, v6, v6
	v_fmac_f32_e32 v5, v4, v4
	v_add_f32_e32 v4, v7, v5
	v_fmamk_f32 v5, v2, 0xbc800000, v65
	v_fmamk_f32 v7, v2, 0xbc800000, v67
	v_add_f32_e32 v3, v3, v4
	v_fmamk_f32 v4, v2, 0xbc800000, v64
	v_fmamk_f32 v6, v2, 0xbc800000, v66
	v_mul_f32_e32 v7, v7, v7
	v_mul_f32_e32 v5, v5, v5
	v_fmac_f32_e32 v7, v6, v6
	v_fmac_f32_e32 v5, v4, v4
	v_add_f32_e32 v4, v7, v5
	v_fmamk_f32 v5, v2, 0xbc800000, v61
	v_fmamk_f32 v7, v2, 0xbc800000, v63
	v_add_f32_e32 v3, v4, v3
	v_fmamk_f32 v4, v2, 0xbc800000, v60
	v_fmamk_f32 v6, v2, 0xbc800000, v62
	v_mul_f32_e32 v7, v7, v7
	v_mul_f32_e32 v5, v5, v5
	v_fmac_f32_e32 v7, v6, v6
	v_fmac_f32_e32 v5, v4, v4
	v_add_f32_e32 v4, v7, v5
	v_add_f32_e32 v3, v4, v3
	v_mov_b32_e32 v4, v3
	s_nop 1
	v_permlane16_swap_b32_e32 v3, v4
	s_waitcnt lgkmcnt(0)
	v_add_f32_e32 v3, v3, v4
	v_mov_b32_e32 v4, v3
	s_nop 1
	v_permlane32_swap_b32_e32 v3, v4
	s_and_saveexec_b64 s[4:5], vcc
	s_cbranch_execz .LBB0_930
	v_mul_f32_e32 v2, 0x3c800000, v2
	s_waitcnt lgkmcnt(0)
	v_add_f32_e32 v3, v3, v4
	ds_write_b64 v34, v[2:3] offset:1024
